# speedup vs baseline: 1.0134x; 1.0081x over previous
; #define LAS __attribute__((address_space(3)))
; __device__ __forceinline__ void ssm_unit(LAS unsigned char* lds, unsigned char* ws, int l, int b, int g, int tid) {
;     ...
;         for (int ct = 0; ct < 17; ++ct) {
;             const int c = ct * 16 + fr, cc = c < 256 ? c : 256;
;             f32x4 acc = (f32x4){0.f, 0.f, 0.f, 0.f};
; #pragma unroll
;             for (int kk = 0; kk < 8; ++kk) { const bf16x8 ub = *(const LAS bf16x8*)(lds + cc * USTR + kk * 64 + fq * 16); acc = __builtin_amdgcn_mfma_f32_16x16x32_bf16(ub, a1[kk], acc, 0, 0, 0); }
;             *(f32x4*)(ET + (size_t)(16 * wid + fr) * ECH + ct * 16 + fq * 4) = acc;
;         }
;     }
;     __syncthreads();
;     if (wid == 0) {
;         float ar, ai; lam_pow(p_lr, p_li, __expf(p_ls), 16.f, ar, ai);
;         float xr = 0.f, xi = 0.f;
;         const float* er = ET + (size_t)lane * ECH; const float* ei = ET + (size_t)(64 + lane) * ECH;
;         f32x4 cr[4], ci[4];
; #pragma unroll
;         for (int q = 0; q < 4; ++q) { cr[q] = *(const f32x4*)(er + q * 4); ci[q] = *(const f32x4*)(ei + q * 4); }
.LBB0_892:
	s_cmpk_lg_i32 s0, 0x400
	s_cselect_b64 vcc, -1, 0
	v_cndmask_b32_e32 v3, v223, v2, vcc
	v_add_u32_e32 v3, v186, v3
	ds_read_b128 v[4:7], v3
	ds_read_b128 v[8:11], v3 offset:64
	v_add_u32_e32 v2, 0x2100, v2
	s_waitcnt lgkmcnt(1)
	v_mfma_f32_16x16x32_bf16 v[4:7], v[4:7], v[178:181], 0
	s_waitcnt lgkmcnt(0)
	v_mfma_f32_16x16x32_bf16 v[4:7], v[8:11], v[154:157], v[4:7]
	ds_read_b128 v[8:11], v3 offset:128
	s_waitcnt lgkmcnt(0)
	v_mfma_f32_16x16x32_bf16 v[4:7], v[8:11], v[158:161], v[4:7]
	ds_read_b128 v[8:11], v3 offset:192
	s_waitcnt lgkmcnt(0)
	v_mfma_f32_16x16x32_bf16 v[4:7], v[8:11], v[162:165], v[4:7]
	ds_read_b128 v[8:11], v3 offset:256
	s_waitcnt lgkmcnt(0)
	v_mfma_f32_16x16x32_bf16 v[4:7], v[8:11], v[166:169], v[4:7]
	ds_read_b128 v[8:11], v3 offset:320
	s_waitcnt lgkmcnt(0)
	v_mfma_f32_16x16x32_bf16 v[4:7], v[8:11], v[170:173], v[4:7]
	ds_read_b128 v[8:11], v3 offset:384
	s_waitcnt lgkmcnt(0)
	v_mfma_f32_16x16x32_bf16 v[4:7], v[8:11], v[174:177], v[4:7]
	ds_read_b128 v[8:11], v3 offset:448
	s_waitcnt lgkmcnt(0)
	v_mfma_f32_16x16x32_bf16 v[4:7], v[8:11], v[182:185], v[4:7]
	v_lshl_add_u64 v[8:9], v[0:1], 0, s[0:1]
	s_add_u32 s0, s0, 64
	s_addc_u32 s1, s1, 0
	s_cmpk_eq_i32 s0, 0x440
	s_nop 3
	global_store_dwordx4 v[8:9], v[4:7], off
	s_cbranch_scc0 .LBB0_892
	s_mul_hi_i32 s1, s76, 0x8800
	s_mul_i32 s0, s76, 0x8800
	s_cmp_lt_u32 s3, 64
	s_waitcnt vmcnt(0)
	s_barrier
	v_mul_f32_e32 v0, 0x3fb8aa3b, v242
	v_exp_f32_e32 v10, v0
	s_mov_b32 s20, 0x394ca1f9
	s_mov_b32 s21, 0x37ccf5ce
	v_mul_f32_e32 v0, v215, v10
	v_mul_f32_e32 v0, 0x41800000, v0
	v_mul_f32_e32 v1, 0x3f22f983, v0
	v_rndne_f32_e32 v1, v1
	v_fmac_f32_e32 v0, 0xbfc90000, v1
	v_fmac_f32_e32 v0, 0xb9fda000, v1
	v_fmac_f32_e32 v0, 0xb3a22169, v1
	v_cvt_i32_f32_e32 v11, v1
	v_mul_f32_e32 v1, v0, v0
	v_mov_b32_e32 v2, v1
	v_pk_fma_f32 v[4:5], v[0:1], s[20:21], v[198:199]
	v_pk_fma_f32 v[8:9], v[2:3], s[20:21], v[200:201] op_sel_hi:[0,1,1] neg_lo:[1,0,0] neg_hi:[1,0,0]
	s_mov_b32 s20, 0xbe2aaaa3
	v_fma_f32 v12, v1, -0.5, 1.0
	v_mov_b32_e32 v9, v5
	s_mov_b32 s21, 0x3d2aaaa5
	v_pk_mul_f32 v[6:7], v[0:1], v[2:3] op_sel_hi:[1,0]
	v_pk_fma_f32 v[2:3], v[2:3], v[8:9], s[20:21] op_sel_hi:[0,1,1]
	v_mov_b32_e32 v1, v12
	v_pk_fma_f32 v[8:9], v[6:7], v[2:3], v[0:1]
	v_and_b32_e32 v0, 3, v11
	v_cmp_lt_i32_e32 vcc, 0, v0
	v_mov_b32_e32 v11, v9
	s_and_saveexec_b64 s[20:21], vcc
	s_cbranch_execz .LBB0_900
	v_cmp_ne_u32_e32 vcc, 1, v0
	v_xor_b32_e32 v11, 0x80000000, v8
	s_and_saveexec_b64 s[22:23], vcc
	s_xor_b64 s[22:23], exec, s[22:23]
	v_cmp_eq_u32_e32 vcc, 2, v0
	s_nop 1
	v_cndmask_b32_e32 v0, v9, v8, vcc
	v_xor_b32_e32 v0, 0x80000000, v0
	v_cndmask_b32_e64 v11, v8, -v9, vcc
	v_mov_b32_e32 v8, v0
	s_andn2_saveexec_b64 s[22:23], s[22:23]
	v_mov_b32_e32 v8, v9
	s_or_b64 exec, exec, s[22:23]
.LBB0_900:
	s_or_b64 exec, exec, s[20:21]
	s_lshl_b64 s[20:21], s[0:1], 2
	s_add_u32 s20, s72, s20
	v_mul_u32_u24_e32 v0, 0x110, v216
	s_addc_u32 s21, s73, s21
	v_lshlrev_b32_e32 v24, 2, v0
	v_lshl_add_u64 v[0:1], s[20:21], 0, v[24:25]
	s_mov_b32 s3, 0x20e9b000
	s_mov_b64 s[20:21], 0x20e9b000
	v_add_co_u32_e32 v2, vcc, s3, v0
	v_lshl_add_u64 v[162:163], v[0:1], 0, s[20:21]
	s_mov_b64 s[20:21], 0x20eac000
	v_addc_co_u32_e32 v3, vcc, 0, v1, vcc
	s_mov_b32 s3, 0x20eac000
	v_lshl_add_u64 v[164:165], v[0:1], 0, s[20:21]
	v_add_co_u32_e32 v0, vcc, s3, v0
	v_addc_co_u32_e32 v1, vcc, 0, v1, vcc
	s_nop 0
	v_mul_f32_e32 v9, v211, v10
	v_mul_f32_e32 v9, 0x41800000, v9
	v_mul_f32_e32 v9, 0x3fb8aa3b, v9
	v_exp_f32_e32 v10, v9
	s_mul_i32 s20, s76, 0x11000
	v_readlane_b32 s22, v254, 40
	s_mul_hi_i32 s3, s76, 0x11000
	v_readlane_b32 s23, v254, 41
	s_add_u32 s20, s22, s20
	s_addc_u32 s3, s23, s3
	v_readlane_b32 s21, v254, 28
	v_mov_b32_e32 v9, v11
	s_add_u32 s20, s21, s20
	v_readlane_b32 s21, v254, 29
	v_pk_mul_f32 v[166:167], v[10:11], v[8:9] op_sel_hi:[0,1]
	v_lshlrev_b32_e32 v24, 2, v216
	s_addc_u32 s21, s21, s3
	v_mov_b32_e32 v168, v166
	v_mov_b32_e32 v169, v166
	v_mov_b32_e32 v170, v167
	v_mov_b32_e32 v171, v167
	v_pk_mov_b32 v[172:173], v[166:167], v[166:167] op_sel:[1,0]
	v_lshl_add_u64 v[174:175], s[20:21], 0, v[24:25]
	v_lshrrev_b32_e32 v14, 6, v201
	v_mov_b32_e32 v10, v167
	v_mov_b32_e32 v11, v166
	v_readfirstlane_b32 s74, v14
	s_lshl_b32 s20, s74, 7
	s_mov_b32 s21, 0
	v_lshl_add_u64 v[4:5], v[162:163], 0, s[20:21]
	v_lshl_add_u64 v[6:7], v[164:165], 0, s[20:21]
	s_lshl_b32 s20, s74, 13
	s_add_i32 s20, s20, 0x800
	v_lshl_add_u64 v[8:9], v[174:175], 0, s[20:21]
	global_load_dwordx4 v[122:125], v[4:5], off
	global_load_dwordx4 v[126:129], v[4:5], off offset:16
	global_load_dwordx4 v[130:133], v[4:5], off offset:32
	global_load_dwordx4 v[134:137], v[4:5], off offset:48
	global_load_dwordx4 v[138:141], v[4:5], off offset:64
	global_load_dwordx4 v[142:145], v[4:5], off offset:80
	global_load_dwordx4 v[146:149], v[4:5], off offset:96
	global_load_dwordx4 v[150:153], v[4:5], off offset:112
	global_load_dwordx4 v[154:157], v[6:7], off
	global_load_dwordx4 v[158:161], v[6:7], off offset:16
	global_load_dwordx4 v[162:165], v[6:7], off offset:32
	global_load_dwordx4 v[166:169], v[6:7], off offset:48
	global_load_dwordx4 v[170:173], v[6:7], off offset:64
	global_load_dwordx4 v[174:177], v[6:7], off offset:80
	global_load_dwordx4 v[178:181], v[6:7], off offset:96
	global_load_dwordx4 v[0:3], v[6:7], off offset:112
	v_mul_f32_e32 v20, v11, v11
	v_mul_f32_e32 v21, v10, v11
	v_fma_f32 v18, v10, v10, -v20
	v_add_f32_e32 v19, v21, v21
	v_mul_f32_e32 v20, v19, v19
	v_mul_f32_e32 v21, v18, v19
	v_fma_f32 v18, v18, v18, -v20
	v_add_f32_e32 v19, v21, v21
	v_mul_f32_e32 v20, v19, v19
	v_mul_f32_e32 v21, v18, v19
	v_fma_f32 v18, v18, v18, -v20
	v_add_f32_e32 v19, v21, v21
	v_mul_f32_e32 v20, v19, v19
	v_mul_f32_e32 v21, v18, v19
	v_fma_f32 v18, v18, v18, -v20
	v_add_f32_e32 v19, v21, v21
	v_mul_f32_e32 v20, v19, v19
	v_mul_f32_e32 v21, v18, v19
	v_fma_f32 v18, v18, v18, -v20
	v_add_f32_e32 v19, v21, v21
	v_mov_b32_e32 v12, 0
	v_mov_b32_e32 v13, 0
	v_lshlrev_b32_e32 v20, 3, v216
	v_add_u32_e32 v20, 0x21400, v20
	s_waitcnt vmcnt(0)
; __device__ __forceinline__ unsigned pk2(float lo, float hi) { unsigned r; asm volatile("v_cvt_pk_bf16_f32 %0, %1, %2" : "=v"(r) : "v"(lo), "v"(hi)); return r; }
; __device__ __forceinline__ void ssm_unit(LAS unsigned char* lds, unsigned char* ws, int l, int b, int g, int tid) {
;     ...
;         for (int sg = 0; sg < 17; ++sg) {
;             f32x4 nr[4], ni[4];
;             const int sn = sg < 16 ? sg + 1 : 16;
; #pragma unroll
;             for (int q = 0; q < 4; ++q) { nr[q] = *(const f32x4*)(er + sn * 16 + q * 4); ni[q] = *(const f32x4*)(ei + sn * 16 + q * 4); }
; #pragma unroll
;             for (int q = 0; q < 4; ++q)
; #pragma unroll
;                 for (int j = 0; j < 4; ++j) { const int c = sg * 16 + q * 4 + j;
;                     if (c <= 256) { *(unsigned*)(XS + (size_t)c * 128 + 2 * lane) = pk2(xr, xi);
;                         const float tr = ar * xr - ai * xi + cr[q][j], ti = ar * xi + ai * xr + ci[q][j]; xr = tr; xi = ti; } }
	v_fma_f32 v14, v10, v12, v122
	v_fma_f32 v15, v10, v13, v154
	v_mov_b32_e32 v122, v12
	v_mov_b32_e32 v154, v13
	v_fma_f32 v12, -v11, v154, v14
	v_fma_f32 v13, v11, v122, v15
	v_fma_f32 v14, v10, v12, v123
	v_fma_f32 v15, v10, v13, v155
	v_mov_b32_e32 v123, v12
	v_mov_b32_e32 v155, v13
	v_fma_f32 v12, -v11, v155, v14
	v_fma_f32 v13, v11, v123, v15
	v_fma_f32 v14, v10, v12, v124
	v_fma_f32 v15, v10, v13, v156
	v_mov_b32_e32 v124, v12
	v_mov_b32_e32 v156, v13
	v_fma_f32 v12, -v11, v156, v14
	v_fma_f32 v13, v11, v124, v15
	v_fma_f32 v14, v10, v12, v125
	v_fma_f32 v15, v10, v13, v157
	v_mov_b32_e32 v125, v12
	v_mov_b32_e32 v157, v13
	v_fma_f32 v12, -v11, v157, v14
	v_fma_f32 v13, v11, v125, v15
	v_fma_f32 v14, v10, v12, v126
	v_fma_f32 v15, v10, v13, v158
	v_mov_b32_e32 v126, v12
	v_mov_b32_e32 v158, v13
	v_fma_f32 v12, -v11, v158, v14
	v_fma_f32 v13, v11, v126, v15
	v_fma_f32 v14, v10, v12, v127
	v_fma_f32 v15, v10, v13, v159
	v_mov_b32_e32 v127, v12
	v_mov_b32_e32 v159, v13
	v_fma_f32 v12, -v11, v159, v14
	v_fma_f32 v13, v11, v127, v15
	v_fma_f32 v14, v10, v12, v128
	v_fma_f32 v15, v10, v13, v160
	v_mov_b32_e32 v128, v12
	v_mov_b32_e32 v160, v13
	v_fma_f32 v12, -v11, v160, v14
	v_fma_f32 v13, v11, v128, v15
	v_fma_f32 v14, v10, v12, v129
	v_fma_f32 v15, v10, v13, v161
	v_mov_b32_e32 v129, v12
	v_mov_b32_e32 v161, v13
	v_fma_f32 v12, -v11, v161, v14
	v_fma_f32 v13, v11, v129, v15
	v_fma_f32 v14, v10, v12, v130
	v_fma_f32 v15, v10, v13, v162
	v_mov_b32_e32 v130, v12
	v_mov_b32_e32 v162, v13
	v_fma_f32 v12, -v11, v162, v14
	v_fma_f32 v13, v11, v130, v15
	v_fma_f32 v14, v10, v12, v131
	v_fma_f32 v15, v10, v13, v163
	v_mov_b32_e32 v131, v12
	v_mov_b32_e32 v163, v13
	v_fma_f32 v12, -v11, v163, v14
	v_fma_f32 v13, v11, v131, v15
	v_fma_f32 v14, v10, v12, v132
	v_fma_f32 v15, v10, v13, v164
	v_mov_b32_e32 v132, v12
	v_mov_b32_e32 v164, v13
	v_fma_f32 v12, -v11, v164, v14
	v_fma_f32 v13, v11, v132, v15
	v_fma_f32 v14, v10, v12, v133
	v_fma_f32 v15, v10, v13, v165
	v_mov_b32_e32 v133, v12
	v_mov_b32_e32 v165, v13
	v_fma_f32 v12, -v11, v165, v14
	v_fma_f32 v13, v11, v133, v15
	v_fma_f32 v14, v10, v12, v134
	v_fma_f32 v15, v10, v13, v166
	v_mov_b32_e32 v134, v12
	v_mov_b32_e32 v166, v13
	v_fma_f32 v12, -v11, v166, v14
	v_fma_f32 v13, v11, v134, v15
	v_fma_f32 v14, v10, v12, v135
	v_fma_f32 v15, v10, v13, v167
	v_mov_b32_e32 v135, v12
	v_mov_b32_e32 v167, v13
	v_fma_f32 v12, -v11, v167, v14
	v_fma_f32 v13, v11, v135, v15
	v_fma_f32 v14, v10, v12, v136
	v_fma_f32 v15, v10, v13, v168
	v_mov_b32_e32 v136, v12
	v_mov_b32_e32 v168, v13
	v_fma_f32 v12, -v11, v168, v14
	v_fma_f32 v13, v11, v136, v15
	v_fma_f32 v14, v10, v12, v137
	v_fma_f32 v15, v10, v13, v169
	v_mov_b32_e32 v137, v12
	v_mov_b32_e32 v169, v13
	v_fma_f32 v12, -v11, v169, v14
	v_fma_f32 v13, v11, v137, v15
	v_fma_f32 v14, v10, v12, v138
	v_fma_f32 v15, v10, v13, v170
	v_mov_b32_e32 v138, v12
	v_mov_b32_e32 v170, v13
	v_fma_f32 v12, -v11, v170, v14
	v_fma_f32 v13, v11, v138, v15
	v_fma_f32 v14, v10, v12, v139
	v_fma_f32 v15, v10, v13, v171
	v_mov_b32_e32 v139, v12
	v_mov_b32_e32 v171, v13
	v_fma_f32 v12, -v11, v171, v14
	v_fma_f32 v13, v11, v139, v15
	v_fma_f32 v14, v10, v12, v140
	v_fma_f32 v15, v10, v13, v172
	v_mov_b32_e32 v140, v12
	v_mov_b32_e32 v172, v13
	v_fma_f32 v12, -v11, v172, v14
	v_fma_f32 v13, v11, v140, v15
	v_fma_f32 v14, v10, v12, v141
	v_fma_f32 v15, v10, v13, v173
	v_mov_b32_e32 v141, v12
	v_mov_b32_e32 v173, v13
	v_fma_f32 v12, -v11, v173, v14
	v_fma_f32 v13, v11, v141, v15
	v_fma_f32 v14, v10, v12, v142
	v_fma_f32 v15, v10, v13, v174
	v_mov_b32_e32 v142, v12
	v_mov_b32_e32 v174, v13
	v_fma_f32 v12, -v11, v174, v14
	v_fma_f32 v13, v11, v142, v15
	v_fma_f32 v14, v10, v12, v143
	v_fma_f32 v15, v10, v13, v175
	v_mov_b32_e32 v143, v12
	v_mov_b32_e32 v175, v13
	v_fma_f32 v12, -v11, v175, v14
	v_fma_f32 v13, v11, v143, v15
	v_fma_f32 v14, v10, v12, v144
	v_fma_f32 v15, v10, v13, v176
	v_mov_b32_e32 v144, v12
	v_mov_b32_e32 v176, v13
	v_fma_f32 v12, -v11, v176, v14
	v_fma_f32 v13, v11, v144, v15
	v_fma_f32 v14, v10, v12, v145
	v_fma_f32 v15, v10, v13, v177
	v_mov_b32_e32 v145, v12
	v_mov_b32_e32 v177, v13
	v_fma_f32 v12, -v11, v177, v14
	v_fma_f32 v13, v11, v145, v15
	v_fma_f32 v14, v10, v12, v146
	v_fma_f32 v15, v10, v13, v178
	v_mov_b32_e32 v146, v12
	v_mov_b32_e32 v178, v13
	v_fma_f32 v12, -v11, v178, v14
	v_fma_f32 v13, v11, v146, v15
	v_fma_f32 v14, v10, v12, v147
	v_fma_f32 v15, v10, v13, v179
	v_mov_b32_e32 v147, v12
	v_mov_b32_e32 v179, v13
	v_fma_f32 v12, -v11, v179, v14
	v_fma_f32 v13, v11, v147, v15
	v_fma_f32 v14, v10, v12, v148
	v_fma_f32 v15, v10, v13, v180
	v_mov_b32_e32 v148, v12
	v_mov_b32_e32 v180, v13
	v_fma_f32 v12, -v11, v180, v14
	v_fma_f32 v13, v11, v148, v15
	v_fma_f32 v14, v10, v12, v149
	v_fma_f32 v15, v10, v13, v181
	v_mov_b32_e32 v149, v12
	v_mov_b32_e32 v181, v13
	v_fma_f32 v12, -v11, v181, v14
	v_fma_f32 v13, v11, v149, v15
	v_fma_f32 v14, v10, v12, v150
	v_fma_f32 v15, v10, v13, v0
	v_mov_b32_e32 v150, v12
	v_mov_b32_e32 v0, v13
	v_fma_f32 v12, -v11, v0, v14
	v_fma_f32 v13, v11, v150, v15
	v_fma_f32 v14, v10, v12, v151
	v_fma_f32 v15, v10, v13, v1
	v_mov_b32_e32 v151, v12
	v_mov_b32_e32 v1, v13
	v_fma_f32 v12, -v11, v1, v14
	v_fma_f32 v13, v11, v151, v15
	v_fma_f32 v14, v10, v12, v152
	v_fma_f32 v15, v10, v13, v2
	v_mov_b32_e32 v152, v12
	v_mov_b32_e32 v2, v13
	v_fma_f32 v12, -v11, v2, v14
	v_fma_f32 v13, v11, v152, v15
	v_fma_f32 v14, v10, v12, v153
	v_fma_f32 v15, v10, v13, v3
	v_mov_b32_e32 v153, v12
	v_mov_b32_e32 v3, v13
	v_fma_f32 v12, -v11, v3, v14
	v_fma_f32 v13, v11, v153, v15
	s_lshl_b32 s20, s74, 9
	v_add_u32_e32 v21, s20, v20
	ds_write_b64 v21, v[12:13]
	s_waitcnt lgkmcnt(0)
	s_barrier
	v_mov_b32_e32 v16, 0
	v_mov_b32_e32 v17, 0
	s_cmp_eq_u32 s74, 0
	s_cbranch_scc1 .Lmy_scan_xdone
	s_mov_b32 s20, 0
; __device__ __forceinline__ unsigned pk2(float lo, float hi) { unsigned r; asm volatile("v_cvt_pk_bf16_f32 %0, %1, %2" : "=v"(r) : "v"(lo), "v"(hi)); return r; }
; __device__ __forceinline__ void ssm_unit(LAS unsigned char* lds, unsigned char* ws, int l, int b, int g, int tid) {
;     ...
;         for (int sg = 0; sg < 17; ++sg) {
;             f32x4 nr[4], ni[4];
;             const int sn = sg < 16 ? sg + 1 : 16;
; #pragma unroll
;             for (int q = 0; q < 4; ++q) { nr[q] = *(const f32x4*)(er + sn * 16 + q * 4); ni[q] = *(const f32x4*)(ei + sn * 16 + q * 4); }
; #pragma unroll
;             for (int q = 0; q < 4; ++q)
; #pragma unroll
;                 for (int j = 0; j < 4; ++j) { const int c = sg * 16 + q * 4 + j;
;                     if (c <= 256) { *(unsigned*)(XS + (size_t)c * 128 + 2 * lane) = pk2(xr, xi);
;                         const float tr = ar * xr - ai * xi + cr[q][j], ti = ar * xi + ai * xr + ci[q][j]; xr = tr; xi = ti; } }
.Lmy_scan_xloop:
	s_lshl_b32 s21, s20, 9
	v_add_u32_e32 v21, s21, v20
	ds_read_b64 v[22:23], v21
	v_mul_f32_e32 v14, v19, v17
	v_mul_f32_e32 v15, v19, v16
	v_fma_f32 v14, v18, v16, -v14
	v_fma_f32 v15, v18, v17, v15
	s_waitcnt lgkmcnt(0)
	v_add_f32_e32 v16, v14, v22
	v_add_f32_e32 v17, v15, v23
	s_add_i32 s20, s20, 1
	s_cmp_lt_u32 s20, s74
	s_cbranch_scc1 .Lmy_scan_xloop
.Lmy_scan_xdone:
	v_add_f32_e32 v14, v122, v16
	v_add_f32_e32 v15, v154, v17
	v_cvt_pk_bf16_f32 v14, v14, v15
	global_store_dword v[8:9], v14, off offset:-4096
	v_mul_f32_e32 v22, v17, v11
	v_mul_f32_e32 v23, v16, v11
	v_fma_f32 v16, v16, v10, -v22
	v_fma_f32 v17, v17, v10, v23
	v_add_f32_e32 v20, v123, v16
	v_add_f32_e32 v15, v155, v17
	v_cvt_pk_bf16_f32 v20, v20, v15
	global_store_dword v[8:9], v20, off offset:-3840
	v_mul_f32_e32 v22, v17, v11
	v_mul_f32_e32 v23, v16, v11
	v_fma_f32 v16, v16, v10, -v22
	v_fma_f32 v17, v17, v10, v23
	v_add_f32_e32 v14, v124, v16
	v_add_f32_e32 v15, v156, v17
	v_cvt_pk_bf16_f32 v14, v14, v15
	global_store_dword v[8:9], v14, off offset:-3584
	v_mul_f32_e32 v22, v17, v11
	v_mul_f32_e32 v23, v16, v11
	v_fma_f32 v16, v16, v10, -v22
	v_fma_f32 v17, v17, v10, v23
	v_add_f32_e32 v20, v125, v16
	v_add_f32_e32 v15, v157, v17
	v_cvt_pk_bf16_f32 v20, v20, v15
	global_store_dword v[8:9], v20, off offset:-3328
	v_mul_f32_e32 v22, v17, v11
	v_mul_f32_e32 v23, v16, v11
	v_fma_f32 v16, v16, v10, -v22
	v_fma_f32 v17, v17, v10, v23
	v_add_f32_e32 v14, v126, v16
	v_add_f32_e32 v15, v158, v17
	v_cvt_pk_bf16_f32 v14, v14, v15
	global_store_dword v[8:9], v14, off offset:-3072
	v_mul_f32_e32 v22, v17, v11
	v_mul_f32_e32 v23, v16, v11
	v_fma_f32 v16, v16, v10, -v22
	v_fma_f32 v17, v17, v10, v23
	v_add_f32_e32 v20, v127, v16
	v_add_f32_e32 v15, v159, v17
	v_cvt_pk_bf16_f32 v20, v20, v15
	global_store_dword v[8:9], v20, off offset:-2816
	v_mul_f32_e32 v22, v17, v11
	v_mul_f32_e32 v23, v16, v11
	v_fma_f32 v16, v16, v10, -v22
	v_fma_f32 v17, v17, v10, v23
	v_add_f32_e32 v14, v128, v16
	v_add_f32_e32 v15, v160, v17
	v_cvt_pk_bf16_f32 v14, v14, v15
	global_store_dword v[8:9], v14, off offset:-2560
	v_mul_f32_e32 v22, v17, v11
	v_mul_f32_e32 v23, v16, v11
	v_fma_f32 v16, v16, v10, -v22
	v_fma_f32 v17, v17, v10, v23
	v_add_f32_e32 v20, v129, v16
	v_add_f32_e32 v15, v161, v17
	v_cvt_pk_bf16_f32 v20, v20, v15
	global_store_dword v[8:9], v20, off offset:-2304
	v_mul_f32_e32 v22, v17, v11
	v_mul_f32_e32 v23, v16, v11
	v_fma_f32 v16, v16, v10, -v22
	v_fma_f32 v17, v17, v10, v23
	v_add_f32_e32 v14, v130, v16
	v_add_f32_e32 v15, v162, v17
	v_cvt_pk_bf16_f32 v14, v14, v15
	global_store_dword v[8:9], v14, off offset:-2048
	v_mul_f32_e32 v22, v17, v11
	v_mul_f32_e32 v23, v16, v11
	v_fma_f32 v16, v16, v10, -v22
	v_fma_f32 v17, v17, v10, v23
	v_add_f32_e32 v20, v131, v16
	v_add_f32_e32 v15, v163, v17
	v_cvt_pk_bf16_f32 v20, v20, v15
	global_store_dword v[8:9], v20, off offset:-1792
	v_mul_f32_e32 v22, v17, v11
	v_mul_f32_e32 v23, v16, v11
	v_fma_f32 v16, v16, v10, -v22
	v_fma_f32 v17, v17, v10, v23
	v_add_f32_e32 v14, v132, v16
	v_add_f32_e32 v15, v164, v17
	v_cvt_pk_bf16_f32 v14, v14, v15
	global_store_dword v[8:9], v14, off offset:-1536
	v_mul_f32_e32 v22, v17, v11
	v_mul_f32_e32 v23, v16, v11
	v_fma_f32 v16, v16, v10, -v22
	v_fma_f32 v17, v17, v10, v23
	v_add_f32_e32 v20, v133, v16
	v_add_f32_e32 v15, v165, v17
	v_cvt_pk_bf16_f32 v20, v20, v15
	global_store_dword v[8:9], v20, off offset:-1280
	v_mul_f32_e32 v22, v17, v11
	v_mul_f32_e32 v23, v16, v11
	v_fma_f32 v16, v16, v10, -v22
	v_fma_f32 v17, v17, v10, v23
	v_add_f32_e32 v14, v134, v16
	v_add_f32_e32 v15, v166, v17
	v_cvt_pk_bf16_f32 v14, v14, v15
	global_store_dword v[8:9], v14, off offset:-1024
	v_mul_f32_e32 v22, v17, v11
	v_mul_f32_e32 v23, v16, v11
	v_fma_f32 v16, v16, v10, -v22
	v_fma_f32 v17, v17, v10, v23
	v_add_f32_e32 v20, v135, v16
	v_add_f32_e32 v15, v167, v17
	v_cvt_pk_bf16_f32 v20, v20, v15
	global_store_dword v[8:9], v20, off offset:-768
	v_mul_f32_e32 v22, v17, v11
	v_mul_f32_e32 v23, v16, v11
	v_fma_f32 v16, v16, v10, -v22
	v_fma_f32 v17, v17, v10, v23
	v_add_f32_e32 v14, v136, v16
	v_add_f32_e32 v15, v168, v17
	v_cvt_pk_bf16_f32 v14, v14, v15
	global_store_dword v[8:9], v14, off offset:-512
	v_mul_f32_e32 v22, v17, v11
	v_mul_f32_e32 v23, v16, v11
	v_fma_f32 v16, v16, v10, -v22
	v_fma_f32 v17, v17, v10, v23
	v_add_f32_e32 v20, v137, v16
	v_add_f32_e32 v15, v169, v17
	v_cvt_pk_bf16_f32 v20, v20, v15
	global_store_dword v[8:9], v20, off offset:-256
	v_mul_f32_e32 v22, v17, v11
	v_mul_f32_e32 v23, v16, v11
	v_fma_f32 v16, v16, v10, -v22
	v_fma_f32 v17, v17, v10, v23
	v_add_f32_e32 v14, v138, v16
	v_add_f32_e32 v15, v170, v17
	v_cvt_pk_bf16_f32 v14, v14, v15
	global_store_dword v[8:9], v14, off
	v_mul_f32_e32 v22, v17, v11
	v_mul_f32_e32 v23, v16, v11
	v_fma_f32 v16, v16, v10, -v22
	v_fma_f32 v17, v17, v10, v23
	v_add_f32_e32 v20, v139, v16
	v_add_f32_e32 v15, v171, v17
	v_cvt_pk_bf16_f32 v20, v20, v15
	global_store_dword v[8:9], v20, off offset:256
	v_mul_f32_e32 v22, v17, v11
	v_mul_f32_e32 v23, v16, v11
	v_fma_f32 v16, v16, v10, -v22
	v_fma_f32 v17, v17, v10, v23
	v_add_f32_e32 v14, v140, v16
	v_add_f32_e32 v15, v172, v17
	v_cvt_pk_bf16_f32 v14, v14, v15
	global_store_dword v[8:9], v14, off offset:512
	v_mul_f32_e32 v22, v17, v11
	v_mul_f32_e32 v23, v16, v11
	v_fma_f32 v16, v16, v10, -v22
	v_fma_f32 v17, v17, v10, v23
	v_add_f32_e32 v20, v141, v16
	v_add_f32_e32 v15, v173, v17
	v_cvt_pk_bf16_f32 v20, v20, v15
	global_store_dword v[8:9], v20, off offset:768
	v_mul_f32_e32 v22, v17, v11
	v_mul_f32_e32 v23, v16, v11
	v_fma_f32 v16, v16, v10, -v22
	v_fma_f32 v17, v17, v10, v23
	v_add_f32_e32 v14, v142, v16
; __device__ __forceinline__ unsigned pk2(float lo, float hi) { unsigned r; asm volatile("v_cvt_pk_bf16_f32 %0, %1, %2" : "=v"(r) : "v"(lo), "v"(hi)); return r; }
; #define SSM_XLOAD(dst, ctq) do { const int c2_ = ((ctq) < 16 ? (ctq) : 16) * 16 + fr, cc2_ = c2_ < 256 ? c2_ : 256; _Pragma("unroll") for (int kk = 0; kk < 4; ++kk) dst[kk] = *(const bf16x8*)(XS + (size_t)cc2_ * 128 + kk * 32 + fq * 8); } while (0)
; __device__ __forceinline__ void ssm_unit(LAS unsigned char* lds, unsigned char* ws, int l, int b, int g, int tid) {
;     ...
;         for (int sg = 0; sg < 17; ++sg) {
;             f32x4 nr[4], ni[4];
;             const int sn = sg < 16 ? sg + 1 : 16;
; #pragma unroll
;             for (int q = 0; q < 4; ++q) { nr[q] = *(const f32x4*)(er + sn * 16 + q * 4); ni[q] = *(const f32x4*)(ei + sn * 16 + q * 4); }
; #pragma unroll
;             for (int q = 0; q < 4; ++q)
; #pragma unroll
;                 for (int j = 0; j < 4; ++j) { const int c = sg * 16 + q * 4 + j;
;                     if (c <= 256) { *(unsigned*)(XS + (size_t)c * 128 + 2 * lane) = pk2(xr, xi);
;                         const float tr = ar * xr - ai * xi + cr[q][j], ti = ar * xi + ai * xr + ci[q][j]; xr = tr; xi = ti; } }
;     ...
;     __syncthreads();
;     {
;         bf16x8 xs[4], x1[4], x2[4];
;     ...
;         SSM_XLOAD(xs, 0); SSM_XLOAD(x1, 1); SSM_XLOAD(x2, 2);
	v_add_f32_e32 v15, v174, v17
	v_cvt_pk_bf16_f32 v14, v14, v15
	global_store_dword v[8:9], v14, off offset:1024
	v_mul_f32_e32 v22, v17, v11
	v_mul_f32_e32 v23, v16, v11
	v_fma_f32 v16, v16, v10, -v22
	v_fma_f32 v17, v17, v10, v23
	v_add_f32_e32 v20, v143, v16
	v_add_f32_e32 v15, v175, v17
	v_cvt_pk_bf16_f32 v20, v20, v15
	global_store_dword v[8:9], v20, off offset:1280
	v_mul_f32_e32 v22, v17, v11
	v_mul_f32_e32 v23, v16, v11
	v_fma_f32 v16, v16, v10, -v22
	v_fma_f32 v17, v17, v10, v23
	v_add_f32_e32 v14, v144, v16
	v_add_f32_e32 v15, v176, v17
	v_cvt_pk_bf16_f32 v14, v14, v15
	global_store_dword v[8:9], v14, off offset:1536
	v_mul_f32_e32 v22, v17, v11
	v_mul_f32_e32 v23, v16, v11
	v_fma_f32 v16, v16, v10, -v22
	v_fma_f32 v17, v17, v10, v23
	v_add_f32_e32 v20, v145, v16
	v_add_f32_e32 v15, v177, v17
	v_cvt_pk_bf16_f32 v20, v20, v15
	global_store_dword v[8:9], v20, off offset:1792
	v_mul_f32_e32 v22, v17, v11
	v_mul_f32_e32 v23, v16, v11
	v_fma_f32 v16, v16, v10, -v22
	v_fma_f32 v17, v17, v10, v23
	v_add_f32_e32 v14, v146, v16
	v_add_f32_e32 v15, v178, v17
	v_cvt_pk_bf16_f32 v14, v14, v15
	global_store_dword v[8:9], v14, off offset:2048
	v_mul_f32_e32 v22, v17, v11
	v_mul_f32_e32 v23, v16, v11
	v_fma_f32 v16, v16, v10, -v22
	v_fma_f32 v17, v17, v10, v23
	v_add_f32_e32 v20, v147, v16
	v_add_f32_e32 v15, v179, v17
	v_cvt_pk_bf16_f32 v20, v20, v15
	global_store_dword v[8:9], v20, off offset:2304
	v_mul_f32_e32 v22, v17, v11
	v_mul_f32_e32 v23, v16, v11
	v_fma_f32 v16, v16, v10, -v22
	v_fma_f32 v17, v17, v10, v23
	v_add_f32_e32 v14, v148, v16
	v_add_f32_e32 v15, v180, v17
	v_cvt_pk_bf16_f32 v14, v14, v15
	global_store_dword v[8:9], v14, off offset:2560
	v_mul_f32_e32 v22, v17, v11
	v_mul_f32_e32 v23, v16, v11
	v_fma_f32 v16, v16, v10, -v22
	v_fma_f32 v17, v17, v10, v23
	v_add_f32_e32 v20, v149, v16
	v_add_f32_e32 v15, v181, v17
	v_cvt_pk_bf16_f32 v20, v20, v15
	global_store_dword v[8:9], v20, off offset:2816
	v_mul_f32_e32 v22, v17, v11
	v_mul_f32_e32 v23, v16, v11
	v_fma_f32 v16, v16, v10, -v22
	v_fma_f32 v17, v17, v10, v23
	v_add_f32_e32 v14, v150, v16
	v_add_f32_e32 v15, v0, v17
	v_cvt_pk_bf16_f32 v14, v14, v15
	global_store_dword v[8:9], v14, off offset:3072
	v_mul_f32_e32 v22, v17, v11
	v_mul_f32_e32 v23, v16, v11
	v_fma_f32 v16, v16, v10, -v22
	v_fma_f32 v17, v17, v10, v23
	v_add_f32_e32 v20, v151, v16
	v_add_f32_e32 v15, v1, v17
	v_cvt_pk_bf16_f32 v20, v20, v15
	global_store_dword v[8:9], v20, off offset:3328
	v_mul_f32_e32 v22, v17, v11
	v_mul_f32_e32 v23, v16, v11
	v_fma_f32 v16, v16, v10, -v22
	v_fma_f32 v17, v17, v10, v23
	v_add_f32_e32 v14, v152, v16
	v_add_f32_e32 v15, v2, v17
	v_cvt_pk_bf16_f32 v14, v14, v15
	global_store_dword v[8:9], v14, off offset:3584
	v_mul_f32_e32 v22, v17, v11
	v_mul_f32_e32 v23, v16, v11
	v_fma_f32 v16, v16, v10, -v22
	v_fma_f32 v17, v17, v10, v23
	v_add_f32_e32 v20, v153, v16
	v_add_f32_e32 v15, v3, v17
	v_cvt_pk_bf16_f32 v20, v20, v15
	global_store_dword v[8:9], v20, off offset:3840
	v_mul_f32_e32 v22, v17, v11
	v_mul_f32_e32 v23, v16, v11
	v_fma_f32 v16, v16, v10, -v22
	v_fma_f32 v17, v17, v10, v23
	s_cmp_lg_u32 s74, 7
	s_cbranch_scc1 .Lmy_scan_done
	v_add_f32_e32 v14, v12, v16
	v_add_f32_e32 v15, v13, v17
	v_cvt_pk_bf16_f32 v14, v14, v15
	s_mov_b64 s[20:21], 0x1000
	v_lshl_add_u64 v[8:9], v[8:9], 0, s[20:21]
	global_store_dword v[8:9], v14, off
.Lmy_scan_done:
.LBB0_932:
	s_waitcnt vmcnt(0)
	s_lshl_b64 s[0:1], s[0:1], 1
	s_add_u32 s0, s72, s0
	s_addc_u32 s1, s73, s1
	s_add_u32 s0, s0, 0x21f9b000
	s_addc_u32 s1, s1, 0
	v_lshlrev_b32_e32 v24, 8, v213
	v_lshl_add_u64 v[0:1], s[0:1], 0, v[24:25]
	v_mov_b32_e32 v211, v25
	v_lshl_add_u64 v[8:9], v[0:1], 0, v[210:211]
	s_movk_i32 s3, 0x2000
	v_add_co_u32_e32 v20, vcc, s3, v8
	v_lshl_add_u64 v[10:11], v[8:9], 0, s[18:19]
	s_nop 0
	v_addc_co_u32_e32 v21, vcc, 0, v9, vcc
	s_mov_b64 s[20:21], 0x2000
	s_barrier
	global_load_dwordx4 v[16:19], v[8:9], off
	global_load_dwordx4 v[12:15], v[8:9], off offset:64
	global_load_dwordx4 v[4:7], v[8:9], off offset:128
	global_load_dwordx4 v[0:3], v[8:9], off offset:192
	global_load_dwordx4 v[122:125], v[10:11], off offset:64
	global_load_dwordx4 v[126:129], v[10:11], off offset:128
	v_lshl_add_u64 v[8:9], v[8:9], 0, s[20:21]
	global_load_dwordx4 v[130:133], v[20:21], off offset:-4096
	global_load_dwordx4 v[134:137], v[20:21], off
	global_load_dwordx4 v[138:141], v[10:11], off offset:192
	global_load_dwordx4 v[142:145], v[8:9], off offset:64
	global_load_dwordx4 v[146:149], v[8:9], off offset:128
	global_load_dwordx4 v[150:153], v[8:9], off offset:192
	s_cmp_lt_u32 s76, 64
	s_cselect_b64 s[20:21], -1, 0
	s_ashr_i32 s3, s2, 31
	v_lshl_add_u64 v[174:175], s[0:1], 0, v[210:211]
	s_lshl_b64 s[0:1], s[2:3], 12
	s_lshl_b32 s2, s24, 5
	s_add_u32 s2, s72, s2
	s_addc_u32 s3, s73, 0
	v_mov_b32_e32 v209, v25
	v_lshl_add_u64 v[8:9], s[2:3], 0, v[208:209]
	s_mov_b64 s[2:3], 0x1fe1b000
	s_cmp_lt_i32 s30, 16
	v_lshl_add_u64 v[176:177], v[8:9], 0, s[2:3]
	s_cselect_b64 s[2:3], -1, 0
	s_cmp_gt_i32 s30, -1
	s_cselect_b64 s[22:23], -1, 0
	s_cmp_lt_i32 s30, 14
	s_cselect_b64 s[24:25], -1, 0
	s_cmp_gt_i32 s30, 1
	s_cselect_b64 s[34:35], -1, 0
	s_cmp_lt_i32 s30, 12
	s_cselect_b64 s[36:37], -1, 0
	s_cmp_gt_i32 s30, 3
	s_cselect_b64 s[38:39], -1, 0
	s_cmp_lt_i32 s30, 10
	s_cselect_b64 s[40:41], -1, 0
	s_cmp_gt_i32 s30, 5
	s_cselect_b64 s[42:43], -1, 0
	s_cmp_lt_i32 s30, 8
	s_cselect_b64 s[44:45], -1, 0
	s_cmp_gt_i32 s30, 7
	s_cselect_b64 s[46:47], -1, 0
	s_cmp_lt_i32 s30, 6
	s_cselect_b64 s[48:49], -1, 0
	s_add_i32 s31, s30, -6
	s_cmp_gt_u32 s31, 3
	s_cselect_b64 s[50:51], -1, 0
	s_cmp_gt_i32 s30, 9
	s_cselect_b64 s[52:53], -1, 0
	s_cmp_lt_i32 s30, 4
	s_cselect_b64 s[54:55], -1, 0
	s_add_i32 s31, s30, -4
	s_cmp_gt_u32 s31, 7
	s_cselect_b64 s[56:57], -1, 0
	s_cmp_gt_i32 s30, 11
	s_cselect_b64 s[58:59], -1, 0
	s_cmp_lt_i32 s30, 2
	s_cselect_b64 s[60:61], -1, 0
	s_add_i32 s31, s30, -2
	s_cmp_gt_u32 s31, 11
	s_cselect_b64 s[62:63], -1, 0
	s_cmp_gt_i32 s30, 13
	s_cselect_b64 s[64:65], -1, 0
	s_add_i32 s67, s30, 0x2000
	s_sub_i32 s71, 0x200f, s30
	s_ashr_i32 s31, s30, 31
	s_ashr_i32 s70, s67, 31
	s_ashr_i32 s72, s71, 31
	s_add_u32 s76, s0, -1
	s_addc_u32 s77, s1, -1
	s_add_u32 s0, s0, s30
	v_lshlrev_b32_e32 v178, 4, v213
	v_mov_b32_e32 v179, v25
	s_addc_u32 s1, s1, s31
	v_lshl_add_u64 v[8:9], s[76:77], 0, v[178:179]
	s_add_u32 s0, s0, -16
	v_mov_b32_e32 v10, s31
	v_subrev_co_u32_e32 v180, vcc, s30, v8
	s_addc_u32 s1, s1, -1
	s_mov_b32 s66, 0
	v_lshl_or_b32 v184, v213, 7, v224
	v_subb_co_u32_e32 v181, vcc, v9, v10, vcc
	v_lshl_add_u64 v[182:183], s[0:1], 0, v[178:179]
	s_mov_b64 s[30:31], 0
	s_branch .LBB0_934
